# placement pin: K-loop heads aligned to 64 bytes (nop-filled, unreachable padding)
# speedup vs baseline: 1.0008x; 1.0008x over previous
;     __host__ __device__ bool next(int i, Unit& u) const { if (!b.next(i >> 1, u)) return false; u.sel = i & 1; return true; }
; #define PG8_STAGE(bufoff, gbase, voff) do { _Pragma("unroll") for (int _i = 0; _i < 2; ++_i) \
;         __builtin_amdgcn_global_load_lds((const unsigned*)((const char*)(gbase) + (voff)[_i]), (PG8_LAS unsigned*)(lds + (bufoff) + ldsw + _i * 8192), 16, 0, 0); } while (0)
; #define PG8_LDA(dst, b, h) do { _Pragma("unroll") for (int m = 0; m < 4; ++m) _Pragma("unroll") for (int k = 0; k < 2; ++k) dst[m][k] = *(const PG8_LAS bf16x8*)(lds + PG8_SA(b, h) + aoff + m * 2048 + k * 1024); } while (0)
; #define PG8_LDB(dst, b, h) do { _Pragma("unroll") for (int n = 0; n < 2; ++n) _Pragma("unroll") for (int k = 0; k < 2; ++k) dst[n][k] = *(const PG8_LAS bf16x8*)(lds + PG8_SB(b, h) + boff + n * 2048 + k * 1024); } while (0)
; #define PG8_MMA(ai, bj, At, Bt) do { __builtin_amdgcn_s_setprio(1); _Pragma("unroll") for (int m = 0; m < 4; ++m) _Pragma("unroll") for (int n = 0; n < 2; ++n) _Pragma("unroll") for (int k = 0; k < 2; ++k) \
;         acc[ai][bj][m][n] = __builtin_amdgcn_mfma_f32_16x16x32_bf16(Bt[n][k], At[m][k], acc[ai][bj][m][n], 0, 0, 0); __builtin_amdgcn_s_setprio(0); } while (0)
; #define PG8_WAIT_V(n) asm volatile("s_waitcnt vmcnt(" #n ")" ::: "memory")
; #define PG8_WAIT_L(n) asm volatile("s_waitcnt lgkmcnt(" #n ")" ::: "memory")
; #define PG8_BAR __builtin_amdgcn_s_barrier()
;     __host__ __device__ bool next(int i, Unit& u) const {
;         const long L = (long)i * G + c; if (L >= nwg) return false;
;         int wgid = (int)L; { const int q = nwg / NXCD, r = nwg % NXCD, xcd = wgid % NXCD, off = wgid / NXCD; wgid = (xcd < r ? xcd * (q + 1) : r * (q + 1) + (xcd - r) * q) + off; }
;         const int nig = WGM * nN, gid = wgid / nig, fm = gid * WGM, gsz = (nM - fm) < WGM ? (nM - fm) : WGM;
;         u.pm = fm + ((wgid % nig) % gsz); u.pn = (wgid % nig) / gsz; u.sel = 0; return true;
; template <class Epi, class Sched, bool ALIGN_EPI = false, bool SP2 = false>
; __device__ __forceinline__ void gemm_phase(PG8_LAS unsigned char* lds, const Gemm g, const Sched& S, const Epi& E) {
;     ...
;             PG8_LDB(B0, 0, 0); PG8_LDB(B1, 0, 1); PG8_SCHED; PG8_LDA(At, 0, 0); PG8_STAGE(PG8_SA(1, 1), a1 + hstep, voffA);
;             PG8_WAIT_V(8); PG8_WAIT_L(0); PG8_BAR; PG8_MMA(0, 0, At, B0); PG8_MMA(0, 1, At, B1); PG8_BAR; PG8_SCHED;
.LBB0_205:
	s_add_u32 s22, s22, 0x40080
	s_addc_u32 s23, s23, 0
	s_add_u32 s52, s24, 0x100
	s_addc_u32 s53, s25, 0
	s_mov_b32 s54, -2
	ds_read_b128 v[154:157], v150
	ds_read_b128 v[158:161], v150 offset:1024
	ds_read_b128 v[162:165], v150 offset:2048
	ds_read_b128 v[166:169], v150 offset:3072
	ds_read_b128 v[170:173], v151
	ds_read_b128 v[174:177], v151 offset:1024
	ds_read_b128 v[178:181], v151 offset:2048
	ds_read_b128 v[182:185], v151 offset:3072
	s_add_u32 s24, s22, 0xfffc0080
	s_addc_u32 s25, s23, -1
	s_cmp_eq_u32 s54, 12
	s_cselect_b32 s27, s15, s25
	s_cselect_b32 s26, s50, s24
	s_cselect_b32 s25, s13, s53
	s_cselect_b32 s24, s51, s52
	v_lshl_add_u64 v[218:219], s[22:23], 0, v[140:141]
	s_add_i32 m0, s37, 0xc000
	ds_read_b128 v[186:189], v152
	ds_read_b128 v[190:193], v152 offset:1024
	ds_read_b128 v[194:197], v152 offset:2048
	ds_read_b128 v[198:201], v152 offset:3072
	ds_read_b128 v[202:205], v152 offset:4096
	ds_read_b128 v[206:209], v152 offset:5120
	ds_read_b128 v[210:213], v152 offset:6144
	ds_read_b128 v[214:217], v152 offset:7168
	global_load_lds_dwordx4 v[218:219], off
	v_lshl_add_u64 v[218:219], s[22:23], 0, v[142:143]
	s_add_i32 m0, s37, 0xe000
	s_nop 0
	global_load_lds_dwordx4 v[218:219], off
	s_add_i32 s44, s44, 1
	s_mul_i32 s0, s44, s46
	s_mul_hi_u32 s1, s44, s33
	s_add_i32 s1, s1, s0
	s_mul_i32 s0, s44, s33
	s_add_u32 s16, s0, s87
	s_addc_u32 s17, s1, s35
	v_cmp_lt_i64_e64 s[0:1], s[16:17], v[144:145]
	s_ashr_i32 s12, s16, 31
	s_lshr_b32 s12, s12, 29
	s_add_i32 s12, s16, s12
	s_ashr_i32 s13, s12, 3
	s_and_b32 s12, s12, -8
	s_sub_i32 s12, s16, s12
	s_cmp_lt_i32 s12, 0
	s_cselect_b32 s14, s36, 0x160
	s_mul_i32 s12, s12, s14
	s_add_i32 s12, s12, s13
	s_mul_hi_i32 s13, s12, 0x2e8ba2e9
	s_lshr_b32 s14, s13, 31
	s_ashr_i32 s13, s13, 3
	s_add_i32 s13, s13, s14
	s_lshl_b32 s14, s13, 1
	s_mul_i32 s13, s13, 44
	s_sub_i32 s13, s12, s13
	s_lshr_b32 s12, s13, 1
	s_and_b32 s13, s13, 1
	s_add_i32 s14, s14, s13
	s_ashr_i32 s15, s14, 31
	s_lshl_b64 s[16:17], s[14:15], 19
	s_add_u32 s16, s28, s16
	s_addc_u32 s17, s29, s17
	s_and_b64 s[18:19], s[0:1], exec
	s_cselect_b32 s15, s17, s29
	s_cselect_b32 s50, s16, s28
	s_ashr_i32 s13, s12, 31
	s_lshl_b64 s[18:19], s[12:13], 19
	s_add_u32 s18, s30, s18
	s_addc_u32 s19, s31, s19
	s_and_b64 s[98:99], s[0:1], exec
	s_cselect_b32 s13, s19, s31
	s_cselect_b32 s51, s18, s30
	s_waitcnt vmcnt(8)
	s_waitcnt lgkmcnt(0)
	s_barrier
	s_setprio 1
	s_waitcnt lgkmcnt(0)
	v_mfma_f32_16x16x32_bf16 v[126:129], v[154:157], v[186:189], 0
	v_mfma_f32_16x16x32_bf16 v[122:125], v[162:165], v[186:189], 0
	v_mfma_f32_16x16x32_bf16 v[110:113], v[154:157], v[194:197], 0
	v_mfma_f32_16x16x32_bf16 v[106:109], v[162:165], v[194:197], 0
	v_mfma_f32_16x16x32_bf16 v[94:97], v[154:157], v[202:205], 0
	v_mfma_f32_16x16x32_bf16 v[90:93], v[162:165], v[202:205], 0
	v_mfma_f32_16x16x32_bf16 v[78:81], v[154:157], v[210:213], 0
	v_mfma_f32_16x16x32_bf16 v[74:77], v[162:165], v[210:213], 0
	v_mfma_f32_16x16x32_bf16 v[126:129], v[158:161], v[190:193], v[126:129]
	v_mfma_f32_16x16x32_bf16 v[122:125], v[166:169], v[190:193], v[122:125]
	v_mfma_f32_16x16x32_bf16 v[110:113], v[158:161], v[198:201], v[110:113]
	v_mfma_f32_16x16x32_bf16 v[106:109], v[166:169], v[198:201], v[106:109]
	v_mfma_f32_16x16x32_bf16 v[94:97], v[158:161], v[206:209], v[94:97]
	v_mfma_f32_16x16x32_bf16 v[90:93], v[166:169], v[206:209], v[90:93]
	v_mfma_f32_16x16x32_bf16 v[78:81], v[158:161], v[214:217], v[78:81]
	v_mfma_f32_16x16x32_bf16 v[74:77], v[166:169], v[214:217], v[74:77]
	s_setprio 0
	s_setprio 1
	v_mfma_f32_16x16x32_bf16 v[118:121], v[170:173], v[186:189], 0
	v_mfma_f32_16x16x32_bf16 v[114:117], v[178:181], v[186:189], 0
	v_mfma_f32_16x16x32_bf16 v[102:105], v[170:173], v[194:197], 0
	v_mfma_f32_16x16x32_bf16 v[98:101], v[178:181], v[194:197], 0
	v_mfma_f32_16x16x32_bf16 v[86:89], v[170:173], v[202:205], 0
	v_mfma_f32_16x16x32_bf16 v[82:85], v[178:181], v[202:205], 0
	v_mfma_f32_16x16x32_bf16 v[70:73], v[170:173], v[210:213], 0
	v_mfma_f32_16x16x32_bf16 v[66:69], v[178:181], v[210:213], 0
	v_mfma_f32_16x16x32_bf16 v[118:121], v[174:177], v[190:193], v[118:121]
	v_mfma_f32_16x16x32_bf16 v[114:117], v[182:185], v[190:193], v[114:117]
	v_mfma_f32_16x16x32_bf16 v[102:105], v[174:177], v[198:201], v[102:105]
	v_mfma_f32_16x16x32_bf16 v[98:101], v[182:185], v[198:201], v[98:101]
	v_mfma_f32_16x16x32_bf16 v[86:89], v[174:177], v[206:209], v[86:89]
	v_mfma_f32_16x16x32_bf16 v[82:85], v[182:185], v[206:209], v[82:85]
	v_mfma_f32_16x16x32_bf16 v[70:73], v[174:177], v[214:217], v[70:73]
	v_mfma_f32_16x16x32_bf16 v[66:69], v[182:185], v[214:217], v[66:69]
	s_setprio 0
	s_barrier
; #define PG8_STAGE(bufoff, gbase, voff) do { _Pragma("unroll") for (int _i = 0; _i < 2; ++_i) \
;         __builtin_amdgcn_global_load_lds((const unsigned*)((const char*)(gbase) + (voff)[_i]), (PG8_LAS unsigned*)(lds + (bufoff) + ldsw + _i * 8192), 16, 0, 0); } while (0)
; #define PG8_LDA(dst, b, h) do { _Pragma("unroll") for (int m = 0; m < 4; ++m) _Pragma("unroll") for (int k = 0; k < 2; ++k) dst[m][k] = *(const PG8_LAS bf16x8*)(lds + PG8_SA(b, h) + aoff + m * 2048 + k * 1024); } while (0)
; #define PG8_MMA(ai, bj, At, Bt) do { __builtin_amdgcn_s_setprio(1); _Pragma("unroll") for (int m = 0; m < 4; ++m) _Pragma("unroll") for (int n = 0; n < 2; ++n) _Pragma("unroll") for (int k = 0; k < 2; ++k) \
;         acc[ai][bj][m][n] = __builtin_amdgcn_mfma_f32_16x16x32_bf16(Bt[n][k], At[m][k], acc[ai][bj][m][n], 0, 0, 0); __builtin_amdgcn_s_setprio(0); } while (0)
; #define PG8_WAIT_V(n) asm volatile("s_waitcnt vmcnt(" #n ")" ::: "memory")
; #define PG8_WAIT_L(n) asm volatile("s_waitcnt lgkmcnt(" #n ")" ::: "memory")
; #define PG8_BAR __builtin_amdgcn_s_barrier()
; #define PG8_SCHED __builtin_amdgcn_sched_barrier(0)
; template <class Epi, class Sched, bool ALIGN_EPI = false, bool SP2 = false>
; __device__ __forceinline__ void gemm_phase(PG8_LAS unsigned char* lds, const Gemm g, const Sched& S, const Epi& E) {
;     ...
;             PG8_LDA(At, 0, 1); PG8_STAGE(PG8_SB(0, 0), b2, voffB); PG8_STAGE(PG8_SB(0, 1), b2 + hstep, voffB); PG8_STAGE(PG8_SA(0, 0), a2, voffA);
;             PG8_WAIT_V(8); PG8_WAIT_L(0); PG8_BAR; PG8_MMA(1, 0, At, B0); PG8_MMA(1, 1, At, B1); PG8_BAR; PG8_SCHED;
	s_add_i32 s55, s47, s34
	v_lshl_add_u64 v[218:219], s[24:25], 0, v[134:135]
	s_mov_b32 m0, s55
	ds_read_b128 v[186:189], v152 offset:16384
	ds_read_b128 v[190:193], v152 offset:17408
	ds_read_b128 v[194:197], v152 offset:18432
	ds_read_b128 v[198:201], v152 offset:19456
	ds_read_b128 v[202:205], v152 offset:20480
	ds_read_b128 v[206:209], v152 offset:21504
	ds_read_b128 v[210:213], v152 offset:22528
	ds_read_b128 v[214:217], v152 offset:23552
	global_load_lds_dwordx4 v[218:219], off
	s_add_i32 m0, s55, 0x2000
	s_add_u32 s56, s24, 0x40000
	v_lshl_add_u64 v[222:223], s[24:25], 0, v[130:131]
	s_addc_u32 s57, s25, 0
	s_add_i32 s55, s48, s34
	global_load_lds_dwordx4 v[222:223], off
	v_lshl_add_u64 v[224:225], s[56:57], 0, v[134:135]
	s_mov_b32 m0, s55
	v_lshl_add_u64 v[226:227], s[26:27], 0, v[132:133]
	global_load_lds_dwordx4 v[224:225], off
	v_lshl_add_u64 v[224:225], s[56:57], 0, v[130:131]
	s_add_i32 m0, s55, 0x2000
	s_nop 0
	global_load_lds_dwordx4 v[224:225], off
	v_lshl_add_u64 v[224:225], s[26:27], 0, v[136:137]
	s_mov_b32 m0, s37
	s_nop 0
	global_load_lds_dwordx4 v[224:225], off
	s_mov_b32 m0, s38
	s_nop 0
	global_load_lds_dwordx4 v[226:227], off
	s_waitcnt vmcnt(8)
	s_waitcnt lgkmcnt(0)
	s_barrier
	s_setprio 1
	s_waitcnt lgkmcnt(0)
	v_mfma_f32_16x16x32_bf16 v[62:65], v[154:157], v[186:189], 0
	v_mfma_f32_16x16x32_bf16 v[58:61], v[162:165], v[186:189], 0
	v_mfma_f32_16x16x32_bf16 v[46:49], v[154:157], v[194:197], 0
	v_mfma_f32_16x16x32_bf16 v[42:45], v[162:165], v[194:197], 0
	v_mfma_f32_16x16x32_bf16 v[30:33], v[154:157], v[202:205], 0
	v_mfma_f32_16x16x32_bf16 v[26:29], v[162:165], v[202:205], 0
	v_mfma_f32_16x16x32_bf16 v[14:17], v[154:157], v[210:213], 0
	v_mfma_f32_16x16x32_bf16 v[10:13], v[162:165], v[210:213], 0
	v_mfma_f32_16x16x32_bf16 v[62:65], v[158:161], v[190:193], v[62:65]
	v_mfma_f32_16x16x32_bf16 v[58:61], v[166:169], v[190:193], v[58:61]
	v_mfma_f32_16x16x32_bf16 v[46:49], v[158:161], v[198:201], v[46:49]
	v_mfma_f32_16x16x32_bf16 v[42:45], v[166:169], v[198:201], v[42:45]
	v_mfma_f32_16x16x32_bf16 v[30:33], v[158:161], v[206:209], v[30:33]
	v_mfma_f32_16x16x32_bf16 v[26:29], v[166:169], v[206:209], v[26:29]
	v_mfma_f32_16x16x32_bf16 v[14:17], v[158:161], v[214:217], v[14:17]
	v_mfma_f32_16x16x32_bf16 v[10:13], v[166:169], v[214:217], v[10:13]
	s_setprio 0
	s_setprio 1
	v_mfma_f32_16x16x32_bf16 v[54:57], v[170:173], v[186:189], 0
	v_mfma_f32_16x16x32_bf16 v[50:53], v[178:181], v[186:189], 0
	v_mfma_f32_16x16x32_bf16 v[38:41], v[170:173], v[194:197], 0
	v_mfma_f32_16x16x32_bf16 v[34:37], v[178:181], v[194:197], 0
	v_mfma_f32_16x16x32_bf16 v[22:25], v[170:173], v[202:205], 0
	v_mfma_f32_16x16x32_bf16 v[18:21], v[178:181], v[202:205], 0
	v_mfma_f32_16x16x32_bf16 v[6:9], v[170:173], v[210:213], 0
	v_mfma_f32_16x16x32_bf16 v[2:5], v[178:181], v[210:213], 0
	v_mfma_f32_16x16x32_bf16 v[54:57], v[174:177], v[190:193], v[54:57]
	v_mfma_f32_16x16x32_bf16 v[50:53], v[182:185], v[190:193], v[50:53]
	v_mfma_f32_16x16x32_bf16 v[38:41], v[174:177], v[198:201], v[38:41]
	v_mfma_f32_16x16x32_bf16 v[34:37], v[182:185], v[198:201], v[34:37]
	v_mfma_f32_16x16x32_bf16 v[22:25], v[174:177], v[206:209], v[22:25]
	v_mfma_f32_16x16x32_bf16 v[18:21], v[182:185], v[206:209], v[18:21]
	v_mfma_f32_16x16x32_bf16 v[6:9], v[174:177], v[214:217], v[6:9]
	v_mfma_f32_16x16x32_bf16 v[2:5], v[182:185], v[214:217], v[2:5]
	s_setprio 0
	s_barrier
	s_branch .Lpz1_mid
	.p2alignl 6, 3212836864

; #define PG8_STAGE(bufoff, gbase, voff) do { _Pragma("unroll") for (int _i = 0; _i < 2; ++_i) \
;         __builtin_amdgcn_global_load_lds((const unsigned*)((const char*)(gbase) + (voff)[_i]), (PG8_LAS unsigned*)(lds + (bufoff) + ldsw + _i * 8192), 16, 0, 0); } while (0)
; #define PG8_LDA(dst, b, h) do { _Pragma("unroll") for (int m = 0; m < 4; ++m) _Pragma("unroll") for (int k = 0; k < 2; ++k) dst[m][k] = *(const PG8_LAS bf16x8*)(lds + PG8_SA(b, h) + aoff + m * 2048 + k * 1024); } while (0)
; #define PG8_LDB(dst, b, h) do { _Pragma("unroll") for (int n = 0; n < 2; ++n) _Pragma("unroll") for (int k = 0; k < 2; ++k) dst[n][k] = *(const PG8_LAS bf16x8*)(lds + PG8_SB(b, h) + boff + n * 2048 + k * 1024); } while (0)
; #define PG8_MMA(ai, bj, At, Bt) do { __builtin_amdgcn_s_setprio(1); _Pragma("unroll") for (int m = 0; m < 4; ++m) _Pragma("unroll") for (int n = 0; n < 2; ++n) _Pragma("unroll") for (int k = 0; k < 2; ++k) \
;         acc[ai][bj][m][n] = __builtin_amdgcn_mfma_f32_16x16x32_bf16(Bt[n][k], At[m][k], acc[ai][bj][m][n], 0, 0, 0); __builtin_amdgcn_s_setprio(0); } while (0)
; #define PG8_WAIT_V(n) asm volatile("s_waitcnt vmcnt(" #n ")" ::: "memory")
; template <class Epi, class Sched, bool ALIGN_EPI = false, bool SP2 = false>
; __device__ __forceinline__ void gemm_phase(PG8_LAS unsigned char* lds, const Gemm g, const Sched& S, const Epi& E) {
;     ...
;             const bool last = (t == nt - 2);
;             const char* a1 = cA + (size_t)(t + 1) * kstepA;
;             const char* a2 = last ? nA : cA + (size_t)(t + 2) * kstepA; const char* b2 = last ? nB : cB + (size_t)(t + 2) * kstep;
;             const char* a3 = a2 + kstepA; const char* b3 = b2 + kstep;
;             if (last && has_next) S.a_ready(nxt);
;             if constexpr (SP2) {
;             PG8_LDB(B0, 0, 0); PG8_LDB(B1, 0, 1); PG8_SCHED; PG8_LDA(At, 0, 0); PG8_STAGE(PG8_SA(1, 1), a1 + hstep, voffA);
;             PG8_WAIT_V(8); PG8_WAIT_L(0); PG8_BAR; PG8_MMA(0, 0, At, B0); PG8_MMA(0, 1, At, B1); PG8_BAR; PG8_SCHED;
;             if constexpr (Epi::PREFETCH) { if (t == tpf) E.prefetch(cur, wid, lane); }
;             PG8_LDA(At, 0, 1); PG8_STAGE(PG8_SB(0, 0), b2, voffB); PG8_STAGE(PG8_SB(0, 1), b2 + hstep, voffB); PG8_STAGE(PG8_SA(0, 0), a2, voffA);
;             PG8_WAIT_V(8); PG8_WAIT_L(0); PG8_BAR; PG8_MMA(1, 0, At, B0); PG8_MMA(1, 1, At, B1); PG8_BAR; PG8_SCHED;
.LBB0_288:
	s_add_u32 s39, s6, 0x100
	s_addc_u32 s40, s7, 0
	s_mov_b32 s41, -2
	ds_read_b128 v[130:133], v223
	ds_read_b128 v[134:137], v223 offset:1024
	ds_read_b128 v[138:141], v223 offset:2048
	ds_read_b128 v[142:145], v223 offset:3072
	ds_read_b128 v[164:167], v224
	ds_read_b128 v[168:171], v224 offset:1024
	ds_read_b128 v[172:175], v224 offset:2048
	ds_read_b128 v[176:179], v224 offset:3072
	s_add_u32 s0, s4, 0x200
	s_addc_u32 s1, s5, 0
	s_cmp_eq_u32 s41, 40
	s_cselect_b32 s37, s31, s1
	s_cselect_b32 s36, s30, s0
	s_cselect_b32 s7, s35, s40
	s_cselect_b32 s6, s34, s39
	v_lshl_add_u64 v[160:161], s[4:5], 0, v[156:157]
	s_add_i32 m0, s51, 0xc000
	ds_read_b128 v[180:183], v225
	ds_read_b128 v[184:187], v225 offset:1024
	ds_read_b128 v[188:191], v225 offset:2048
	ds_read_b128 v[192:195], v225 offset:3072
	ds_read_b128 v[196:199], v225 offset:4096
	ds_read_b128 v[200:203], v225 offset:5120
	ds_read_b128 v[204:207], v225 offset:6144
	ds_read_b128 v[208:211], v225 offset:7168
	global_load_lds_dwordx4 v[160:161], off
	v_lshl_add_u64 v[160:161], s[4:5], 0, v[158:159]
	s_add_i32 m0, s51, 0xe000
	s_nop 0
	global_load_lds_dwordx4 v[160:161], off
	s_waitcnt vmcnt(8)
	s_waitcnt lgkmcnt(0)
	s_barrier
	s_setprio 1
	s_waitcnt lgkmcnt(0)
	v_mfma_f32_16x16x32_bf16 v[126:129], v[130:133], v[180:183], 0
	v_mfma_f32_16x16x32_bf16 v[122:125], v[138:141], v[180:183], 0
	v_mfma_f32_16x16x32_bf16 v[110:113], v[130:133], v[188:191], 0
	v_mfma_f32_16x16x32_bf16 v[106:109], v[138:141], v[188:191], 0
	v_mfma_f32_16x16x32_bf16 v[94:97], v[130:133], v[196:199], 0
	v_mfma_f32_16x16x32_bf16 v[90:93], v[138:141], v[196:199], 0
	v_mfma_f32_16x16x32_bf16 v[78:81], v[130:133], v[204:207], 0
	v_mfma_f32_16x16x32_bf16 v[74:77], v[138:141], v[204:207], 0
	v_mfma_f32_16x16x32_bf16 v[126:129], v[134:137], v[184:187], v[126:129]
	v_mfma_f32_16x16x32_bf16 v[122:125], v[142:145], v[184:187], v[122:125]
	v_mfma_f32_16x16x32_bf16 v[110:113], v[134:137], v[192:195], v[110:113]
	v_mfma_f32_16x16x32_bf16 v[106:109], v[142:145], v[192:195], v[106:109]
	v_mfma_f32_16x16x32_bf16 v[94:97], v[134:137], v[200:203], v[94:97]
	v_mfma_f32_16x16x32_bf16 v[90:93], v[142:145], v[200:203], v[90:93]
	v_mfma_f32_16x16x32_bf16 v[78:81], v[134:137], v[208:211], v[78:81]
	v_mfma_f32_16x16x32_bf16 v[74:77], v[142:145], v[208:211], v[74:77]
	s_setprio 0
	s_setprio 1
	v_mfma_f32_16x16x32_bf16 v[118:121], v[164:167], v[180:183], 0
	v_mfma_f32_16x16x32_bf16 v[114:117], v[172:175], v[180:183], 0
	v_mfma_f32_16x16x32_bf16 v[102:105], v[164:167], v[188:191], 0
	v_mfma_f32_16x16x32_bf16 v[98:101], v[172:175], v[188:191], 0
	v_mfma_f32_16x16x32_bf16 v[86:89], v[164:167], v[196:199], 0
	v_mfma_f32_16x16x32_bf16 v[82:85], v[172:175], v[196:199], 0
	v_mfma_f32_16x16x32_bf16 v[70:73], v[164:167], v[204:207], 0
	v_mfma_f32_16x16x32_bf16 v[66:69], v[172:175], v[204:207], 0
	v_mfma_f32_16x16x32_bf16 v[118:121], v[168:171], v[184:187], v[118:121]
	v_mfma_f32_16x16x32_bf16 v[114:117], v[176:179], v[184:187], v[114:117]
	v_mfma_f32_16x16x32_bf16 v[102:105], v[168:171], v[192:195], v[102:105]
	v_mfma_f32_16x16x32_bf16 v[98:101], v[176:179], v[192:195], v[98:101]
	v_mfma_f32_16x16x32_bf16 v[86:89], v[168:171], v[200:203], v[86:89]
	v_mfma_f32_16x16x32_bf16 v[82:85], v[176:179], v[200:203], v[82:85]
	v_mfma_f32_16x16x32_bf16 v[70:73], v[168:171], v[208:211], v[70:73]
	v_mfma_f32_16x16x32_bf16 v[66:69], v[176:179], v[208:211], v[66:69]
	s_setprio 0
	s_barrier
	s_add_i32 s4, s68, s50
	v_lshl_add_u64 v[160:161], s[6:7], 0, v[148:149]
	s_mov_b32 m0, s4
	ds_read_b128 v[180:183], v225 offset:16384
	ds_read_b128 v[184:187], v225 offset:17408
	ds_read_b128 v[188:191], v225 offset:18432
	ds_read_b128 v[192:195], v225 offset:19456
	ds_read_b128 v[196:199], v225 offset:20480
	ds_read_b128 v[200:203], v225 offset:21504
	ds_read_b128 v[204:207], v225 offset:22528
	ds_read_b128 v[208:211], v225 offset:23552
	global_load_lds_dwordx4 v[160:161], off
	s_add_i32 m0, s4, 0x2000
	s_add_u32 s4, s6, 0xb0000
	v_lshl_add_u64 v[162:163], s[6:7], 0, v[152:153]
	s_addc_u32 s5, s7, 0
	s_add_i32 s42, s69, s50
	global_load_lds_dwordx4 v[162:163], off
	v_lshl_add_u64 v[212:213], s[4:5], 0, v[148:149]
	s_mov_b32 m0, s42
	v_lshl_add_u64 v[214:215], s[36:37], 0, v[150:151]
	global_load_lds_dwordx4 v[212:213], off
	v_lshl_add_u64 v[212:213], s[4:5], 0, v[152:153]
	s_add_i32 m0, s42, 0x2000
	s_nop 0
	global_load_lds_dwordx4 v[212:213], off
	v_lshl_add_u64 v[212:213], s[36:37], 0, v[146:147]
	s_mov_b32 m0, s51
	s_nop 0
	global_load_lds_dwordx4 v[212:213], off
	s_mov_b32 m0, s52
	s_nop 0
	global_load_lds_dwordx4 v[214:215], off
	s_waitcnt vmcnt(8)
	s_waitcnt lgkmcnt(0)
	s_barrier
	s_setprio 1
	s_waitcnt lgkmcnt(0)
	v_mfma_f32_16x16x32_bf16 v[62:65], v[130:133], v[180:183], 0
	v_mfma_f32_16x16x32_bf16 v[58:61], v[138:141], v[180:183], 0
	v_mfma_f32_16x16x32_bf16 v[46:49], v[130:133], v[188:191], 0
	v_mfma_f32_16x16x32_bf16 v[42:45], v[138:141], v[188:191], 0
	v_mfma_f32_16x16x32_bf16 v[30:33], v[130:133], v[196:199], 0
	v_mfma_f32_16x16x32_bf16 v[26:29], v[138:141], v[196:199], 0
	v_mfma_f32_16x16x32_bf16 v[14:17], v[130:133], v[204:207], 0
	v_mfma_f32_16x16x32_bf16 v[10:13], v[138:141], v[204:207], 0
	v_mfma_f32_16x16x32_bf16 v[62:65], v[134:137], v[184:187], v[62:65]
	v_mfma_f32_16x16x32_bf16 v[58:61], v[142:145], v[184:187], v[58:61]
	v_mfma_f32_16x16x32_bf16 v[46:49], v[134:137], v[192:195], v[46:49]
	v_mfma_f32_16x16x32_bf16 v[42:45], v[142:145], v[192:195], v[42:45]
	v_mfma_f32_16x16x32_bf16 v[30:33], v[134:137], v[200:203], v[30:33]
	v_mfma_f32_16x16x32_bf16 v[26:29], v[142:145], v[200:203], v[26:29]
	v_mfma_f32_16x16x32_bf16 v[14:17], v[134:137], v[208:211], v[14:17]
	v_mfma_f32_16x16x32_bf16 v[10:13], v[142:145], v[208:211], v[10:13]
	s_setprio 0
	s_setprio 1
	v_mfma_f32_16x16x32_bf16 v[54:57], v[164:167], v[180:183], 0
	v_mfma_f32_16x16x32_bf16 v[50:53], v[172:175], v[180:183], 0
	v_mfma_f32_16x16x32_bf16 v[38:41], v[164:167], v[188:191], 0
	v_mfma_f32_16x16x32_bf16 v[34:37], v[172:175], v[188:191], 0
	v_mfma_f32_16x16x32_bf16 v[22:25], v[164:167], v[196:199], 0
	v_mfma_f32_16x16x32_bf16 v[18:21], v[172:175], v[196:199], 0
	v_mfma_f32_16x16x32_bf16 v[6:9], v[164:167], v[204:207], 0
	v_mfma_f32_16x16x32_bf16 v[2:5], v[172:175], v[204:207], 0
	v_mfma_f32_16x16x32_bf16 v[54:57], v[168:171], v[184:187], v[54:57]
	v_mfma_f32_16x16x32_bf16 v[50:53], v[176:179], v[184:187], v[50:53]
	v_mfma_f32_16x16x32_bf16 v[38:41], v[168:171], v[192:195], v[38:41]
	v_mfma_f32_16x16x32_bf16 v[34:37], v[176:179], v[192:195], v[34:37]
	v_mfma_f32_16x16x32_bf16 v[22:25], v[168:171], v[200:203], v[22:25]
	v_mfma_f32_16x16x32_bf16 v[18:21], v[176:179], v[200:203], v[18:21]
	v_mfma_f32_16x16x32_bf16 v[6:9], v[168:171], v[208:211], v[6:9]
	v_mfma_f32_16x16x32_bf16 v[2:5], v[176:179], v[208:211], v[2:5]
	s_setprio 0
	s_barrier
	s_branch .Lpz2_mid
	.p2alignl 6, 3212836864

; #define PG8_STAGE(bufoff, gbase, voff) do { _Pragma("unroll") for (int _i = 0; _i < 2; ++_i) \
;         __builtin_amdgcn_global_load_lds((const unsigned*)((const char*)(gbase) + (voff)[_i]), (PG8_LAS unsigned*)(lds + (bufoff) + ldsw + _i * 8192), 16, 0, 0); } while (0)
; #define PG8_LDA(dst, b, h) do { _Pragma("unroll") for (int m = 0; m < 4; ++m) _Pragma("unroll") for (int k = 0; k < 2; ++k) dst[m][k] = *(const PG8_LAS bf16x8*)(lds + PG8_SA(b, h) + aoff + m * 2048 + k * 1024); } while (0)
; #define PG8_LDB(dst, b, h) do { _Pragma("unroll") for (int n = 0; n < 2; ++n) _Pragma("unroll") for (int k = 0; k < 2; ++k) dst[n][k] = *(const PG8_LAS bf16x8*)(lds + PG8_SB(b, h) + boff + n * 2048 + k * 1024); } while (0)
; #define PG8_MMA(ai, bj, At, Bt) do { __builtin_amdgcn_s_setprio(1); _Pragma("unroll") for (int m = 0; m < 4; ++m) _Pragma("unroll") for (int n = 0; n < 2; ++n) _Pragma("unroll") for (int k = 0; k < 2; ++k) \
;         acc[ai][bj][m][n] = __builtin_amdgcn_mfma_f32_16x16x32_bf16(Bt[n][k], At[m][k], acc[ai][bj][m][n], 0, 0, 0); __builtin_amdgcn_s_setprio(0); } while (0)
; #define PG8_WAIT_V(n) asm volatile("s_waitcnt vmcnt(" #n ")" ::: "memory")
; #define PG8_WAIT_L(n) asm volatile("s_waitcnt lgkmcnt(" #n ")" ::: "memory")
; #define PG8_BAR __builtin_amdgcn_s_barrier()
; template <class Epi, class Sched, bool ALIGN_EPI = false, bool SP2 = false>
; __device__ __forceinline__ void gemm_phase(PG8_LAS unsigned char* lds, const Gemm g, const Sched& S, const Epi& E) {
;     ...
;             const char* a2 = last ? nA : cA + (size_t)(t + 2) * kstepA; const char* b2 = last ? nB : cB + (size_t)(t + 2) * kstep;
;             const char* a3 = a2 + kstepA; const char* b3 = b2 + kstep;
;             if (last && has_next) S.a_ready(nxt);
;             if constexpr (SP2) {
;             PG8_LDB(B0, 0, 0); PG8_LDB(B1, 0, 1); PG8_SCHED; PG8_LDA(At, 0, 0); PG8_STAGE(PG8_SA(1, 1), a1 + hstep, voffA);
;             PG8_WAIT_V(8); PG8_WAIT_L(0); PG8_BAR; PG8_MMA(0, 0, At, B0); PG8_MMA(0, 1, At, B1); PG8_BAR; PG8_SCHED;
;             if constexpr (Epi::PREFETCH) { if (t == tpf) E.prefetch(cur, wid, lane); }
;             PG8_LDA(At, 0, 1); PG8_STAGE(PG8_SB(0, 0), b2, voffB); PG8_STAGE(PG8_SB(0, 1), b2 + hstep, voffB); PG8_STAGE(PG8_SA(0, 0), a2, voffA);
;             PG8_WAIT_V(8); PG8_WAIT_L(0); PG8_BAR; PG8_MMA(1, 0, At, B0); PG8_MMA(1, 1, At, B1); PG8_BAR; PG8_SCHED;
.Lpz3_a:
	s_add_u32 s29, s10, s56
	s_addc_u32 s58, s11, s57
	s_add_u32 s29, s29, 0x100
	s_addc_u32 s58, s58, 0
	s_add_u32 vcc_lo, s5, s56
	s_addc_u32 s59, s9, s57
	s_cmpk_eq_i32 s56, 0x700
	s_cselect_b32 s61, s7, s58
	s_cselect_b32 s59, s45, s59
	s_cselect_b32 s58, s47, vcc_lo
	s_mov_b32 m0, s70
	s_cselect_b32 s60, s31, s29
	v_lshl_add_u64 v[204:205], s[58:59], 0, v[180:181]
	s_add_u32 vcc_lo, s58, 0x40000
	ds_read_b128 v[122:125], v210 offset:16384
	ds_read_b128 v[126:129], v210 offset:17408
	ds_read_b128 v[138:141], v210 offset:18432
	ds_read_b128 v[142:145], v210 offset:19456
	ds_read_b128 v[212:215], v210 offset:20480
	ds_read_b128 v[216:219], v210 offset:21504
	ds_read_b128 v[222:225], v210 offset:22528
	ds_read_b128 v[226:229], v210 offset:23552
	global_load_lds_dwordx4 v[204:205], off
	v_lshl_add_u64 v[246:247], s[58:59], 0, v[184:185]
	s_mov_b32 m0, s71
	s_addc_u32 vcc_hi, s59, 0
	global_load_lds_dwordx4 v[246:247], off
	v_lshl_add_u64 v[230:231], vcc, 0, v[180:181]
	s_mov_b32 m0, s72
	v_lshl_add_u64 v[248:249], s[60:61], 0, v[178:179]
	global_load_lds_dwordx4 v[230:231], off
	v_lshl_add_u64 v[230:231], vcc, 0, v[184:185]
	s_mov_b32 m0, s73
	v_lshl_add_u64 v[250:251], s[60:61], 0, v[182:183]
	global_load_lds_dwordx4 v[230:231], off
	s_mov_b32 m0, s69
	s_nop 0
	global_load_lds_dwordx4 v[248:249], off
	s_mov_b32 m0, s74
	s_nop 0
	global_load_lds_dwordx4 v[250:251], off
	s_waitcnt vmcnt(8)
	s_waitcnt lgkmcnt(0)
	s_barrier
	s_setprio 1
	s_waitcnt lgkmcnt(0)
	v_mfma_f32_16x16x32_bf16 v[78:81], v[162:165], v[122:125], 0
	v_mfma_f32_16x16x32_bf16 v[74:77], v[170:173], v[122:125], 0
	v_mfma_f32_16x16x32_bf16 v[62:65], v[162:165], v[138:141], 0
	v_mfma_f32_16x16x32_bf16 v[58:61], v[170:173], v[138:141], 0
	v_mfma_f32_16x16x32_bf16 v[30:33], v[162:165], v[212:215], 0
	v_mfma_f32_16x16x32_bf16 v[26:29], v[170:173], v[212:215], 0
	v_mfma_f32_16x16x32_bf16 v[14:17], v[162:165], v[222:225], 0
	v_mfma_f32_16x16x32_bf16 v[10:13], v[170:173], v[222:225], 0
	v_mfma_f32_16x16x32_bf16 v[78:81], v[166:169], v[126:129], v[78:81]
	v_mfma_f32_16x16x32_bf16 v[74:77], v[174:177], v[126:129], v[74:77]
	v_mfma_f32_16x16x32_bf16 v[62:65], v[166:169], v[142:145], v[62:65]
	v_mfma_f32_16x16x32_bf16 v[58:61], v[174:177], v[142:145], v[58:61]
	v_mfma_f32_16x16x32_bf16 v[30:33], v[166:169], v[216:219], v[30:33]
	v_mfma_f32_16x16x32_bf16 v[26:29], v[174:177], v[216:219], v[26:29]
	v_mfma_f32_16x16x32_bf16 v[14:17], v[166:169], v[226:229], v[14:17]
	v_mfma_f32_16x16x32_bf16 v[10:13], v[174:177], v[226:229], v[10:13]
	s_setprio 0
	s_setprio 1
	v_mfma_f32_16x16x32_bf16 v[70:73], v[146:149], v[122:125], 0
	v_mfma_f32_16x16x32_bf16 v[66:69], v[154:157], v[122:125], 0
	v_mfma_f32_16x16x32_bf16 v[38:41], v[146:149], v[138:141], 0
	v_mfma_f32_16x16x32_bf16 v[34:37], v[154:157], v[138:141], 0
	v_mfma_f32_16x16x32_bf16 v[22:25], v[146:149], v[212:215], 0
	v_mfma_f32_16x16x32_bf16 v[18:21], v[154:157], v[212:215], 0
	v_mfma_f32_16x16x32_bf16 v[6:9], v[146:149], v[222:225], 0
	v_mfma_f32_16x16x32_bf16 v[2:5], v[154:157], v[222:225], 0
	v_mfma_f32_16x16x32_bf16 v[70:73], v[150:153], v[126:129], v[70:73]
	v_mfma_f32_16x16x32_bf16 v[66:69], v[158:161], v[126:129], v[66:69]
	v_mfma_f32_16x16x32_bf16 v[38:41], v[150:153], v[142:145], v[38:41]
	v_mfma_f32_16x16x32_bf16 v[34:37], v[158:161], v[142:145], v[34:37]
	v_mfma_f32_16x16x32_bf16 v[22:25], v[150:153], v[216:219], v[22:25]
	v_mfma_f32_16x16x32_bf16 v[18:21], v[158:161], v[216:219], v[18:21]
	v_mfma_f32_16x16x32_bf16 v[6:9], v[150:153], v[226:229], v[6:9]
	v_mfma_f32_16x16x32_bf16 v[2:5], v[158:161], v[226:229], v[2:5]
	s_setprio 0
	s_barrier
	s_branch .Lpz3_mid
	.p2alignl 6, 3212836864

;     __host__ __device__ bool next(int i, Unit& u) const { if (!b.next(i >> 1, u)) return false; u.sel = i & 1; return true; }
; #define PG8_STAGE(bufoff, gbase, voff) do { _Pragma("unroll") for (int _i = 0; _i < 2; ++_i) \
;         __builtin_amdgcn_global_load_lds((const unsigned*)((const char*)(gbase) + (voff)[_i]), (PG8_LAS unsigned*)(lds + (bufoff) + ldsw + _i * 8192), 16, 0, 0); } while (0)
; #define PG8_LDA(dst, b, h) do { _Pragma("unroll") for (int m = 0; m < 4; ++m) _Pragma("unroll") for (int k = 0; k < 2; ++k) dst[m][k] = *(const PG8_LAS bf16x8*)(lds + PG8_SA(b, h) + aoff + m * 2048 + k * 1024); } while (0)
; #define PG8_LDB(dst, b, h) do { _Pragma("unroll") for (int n = 0; n < 2; ++n) _Pragma("unroll") for (int k = 0; k < 2; ++k) dst[n][k] = *(const PG8_LAS bf16x8*)(lds + PG8_SB(b, h) + boff + n * 2048 + k * 1024); } while (0)
; #define PG8_MMA(ai, bj, At, Bt) do { __builtin_amdgcn_s_setprio(1); _Pragma("unroll") for (int m = 0; m < 4; ++m) _Pragma("unroll") for (int n = 0; n < 2; ++n) _Pragma("unroll") for (int k = 0; k < 2; ++k) \
;         acc[ai][bj][m][n] = __builtin_amdgcn_mfma_f32_16x16x32_bf16(Bt[n][k], At[m][k], acc[ai][bj][m][n], 0, 0, 0); __builtin_amdgcn_s_setprio(0); } while (0)
; #define PG8_WAIT_V(n) asm volatile("s_waitcnt vmcnt(" #n ")" ::: "memory")
; #define PG8_BAR __builtin_amdgcn_s_barrier()
; template <class Epi, class Sched, bool ALIGN_EPI = false, bool SP2 = false>
; __device__ __forceinline__ void gemm_phase(PG8_LAS unsigned char* lds, const Gemm g, const Sched& S, const Epi& E) {
;     ...
;         const bool has_next = S.next(ui + 1, nxt);
;         const char* nA = has_next ? PG8_ABASE(nxt) : cA; const char* nB = has_next ? PG8_BBASE(nxt) : cB;
;         for (int t = 0; t < nt; t += 2) {
;             const bool last = (t == nt - 2);
;             const char* a1 = cA + (size_t)(t + 1) * kstepA;
;             const char* a2 = last ? nA : cA + (size_t)(t + 2) * kstepA; const char* b2 = last ? nB : cB + (size_t)(t + 2) * kstep;
;             const char* a3 = a2 + kstepA; const char* b3 = b2 + kstep;
;             if (last && has_next) S.a_ready(nxt);
;             if constexpr (SP2) {
;             PG8_LDB(B0, 0, 0); PG8_LDB(B1, 0, 1); PG8_SCHED; PG8_LDA(At, 0, 0); PG8_STAGE(PG8_SA(1, 1), a1 + hstep, voffA);
;             PG8_WAIT_V(8); PG8_WAIT_L(0); PG8_BAR; PG8_MMA(0, 0, At, B0); PG8_MMA(0, 1, At, B1); PG8_BAR; PG8_SCHED;
.LBB0_837:
	s_ashr_i32 s29, s28, 31
	s_lshl_b64 s[30:31], s[28:29], 19
	s_add_u32 s30, s46, s30
	s_addc_u32 s31, s47, s31
	s_and_b64 s[34:35], s[2:3], exec
	s_cselect_b32 s1, s31, s5
	s_cselect_b32 s29, s30, s4
	s_ashr_i32 s27, s26, 31
	s_lshl_b64 s[34:35], s[26:27], 19
	s_add_u32 s34, s48, s34
	s_addc_u32 s35, s49, s35
	s_and_b64 s[36:37], s[2:3], exec
	s_cselect_b32 s27, s35, s7
	s_cselect_b32 s38, s34, s6
	s_add_u32 s4, s4, 0x40080
	s_addc_u32 s5, s5, 0
	s_add_u32 s39, s6, 0x100
	s_addc_u32 s40, s7, 0
	s_mov_b32 s41, -2
	s_waitcnt lgkmcnt(0)
	ds_read_b128 v[50:53], v214
	ds_read_b128 v[54:57], v214 offset:1024
	ds_read_b128 v[66:69], v214 offset:2048
	ds_read_b128 v[70:73], v214 offset:3072
	ds_read_b128 v[146:149], v215
	ds_read_b128 v[150:153], v215 offset:1024
	ds_read_b128 v[172:175], v215 offset:2048
	ds_read_b128 v[176:179], v215 offset:3072
	s_add_u32 s6, s4, 0xfffc0080
	s_addc_u32 s7, s5, -1
	s_cmp_eq_u32 s41, 12
	s_cselect_b32 s37, s1, s7
	s_cselect_b32 s36, s29, s6
	s_cselect_b32 s7, s27, s40
	s_cselect_b32 s6, s38, s39
	v_lshl_add_u64 v[218:219], s[4:5], 0, v[164:165]
	s_add_i32 m0, s51, 0xc000
	ds_read_b128 v[180:183], v216
	ds_read_b128 v[184:187], v216 offset:1024
	ds_read_b128 v[188:191], v216 offset:2048
	ds_read_b128 v[192:195], v216 offset:3072
	ds_read_b128 v[196:199], v216 offset:4096
	ds_read_b128 v[200:203], v216 offset:5120
	ds_read_b128 v[204:207], v216 offset:6144
	ds_read_b128 v[208:211], v216 offset:7168
	global_load_lds_dwordx4 v[218:219], off
	v_lshl_add_u64 v[218:219], s[4:5], 0, v[166:167]
	s_add_i32 m0, s51, 0xe000
	s_nop 0
	global_load_lds_dwordx4 v[218:219], off
	s_waitcnt vmcnt(8)
	s_waitcnt lgkmcnt(0)
	s_barrier
	s_setprio 1
	s_waitcnt lgkmcnt(0)
	v_mfma_f32_16x16x32_bf16 v[142:145], v[50:53], v[180:183], 0
	v_mfma_f32_16x16x32_bf16 v[138:141], v[66:69], v[180:183], 0
	v_mfma_f32_16x16x32_bf16 v[126:129], v[50:53], v[188:191], 0
	v_mfma_f32_16x16x32_bf16 v[122:125], v[66:69], v[188:191], 0
	v_mfma_f32_16x16x32_bf16 v[110:113], v[50:53], v[196:199], 0
	v_mfma_f32_16x16x32_bf16 v[106:109], v[66:69], v[196:199], 0
	v_mfma_f32_16x16x32_bf16 v[94:97], v[50:53], v[204:207], 0
	v_mfma_f32_16x16x32_bf16 v[90:93], v[66:69], v[204:207], 0
	v_mfma_f32_16x16x32_bf16 v[142:145], v[54:57], v[184:187], v[142:145]
	v_mfma_f32_16x16x32_bf16 v[138:141], v[70:73], v[184:187], v[138:141]
	v_mfma_f32_16x16x32_bf16 v[126:129], v[54:57], v[192:195], v[126:129]
	v_mfma_f32_16x16x32_bf16 v[122:125], v[70:73], v[192:195], v[122:125]
	v_mfma_f32_16x16x32_bf16 v[110:113], v[54:57], v[200:203], v[110:113]
	v_mfma_f32_16x16x32_bf16 v[106:109], v[70:73], v[200:203], v[106:109]
	v_mfma_f32_16x16x32_bf16 v[94:97], v[54:57], v[208:211], v[94:97]
	v_mfma_f32_16x16x32_bf16 v[90:93], v[70:73], v[208:211], v[90:93]
	s_setprio 0
	s_setprio 1
	v_mfma_f32_16x16x32_bf16 v[134:137], v[146:149], v[180:183], 0
	v_mfma_f32_16x16x32_bf16 v[130:133], v[172:175], v[180:183], 0
	v_mfma_f32_16x16x32_bf16 v[118:121], v[146:149], v[188:191], 0
	v_mfma_f32_16x16x32_bf16 v[114:117], v[172:175], v[188:191], 0
	v_mfma_f32_16x16x32_bf16 v[102:105], v[146:149], v[196:199], 0
	v_mfma_f32_16x16x32_bf16 v[98:101], v[172:175], v[196:199], 0
	v_mfma_f32_16x16x32_bf16 v[86:89], v[146:149], v[204:207], 0
	v_mfma_f32_16x16x32_bf16 v[82:85], v[172:175], v[204:207], 0
	v_mfma_f32_16x16x32_bf16 v[134:137], v[150:153], v[184:187], v[134:137]
	v_mfma_f32_16x16x32_bf16 v[130:133], v[176:179], v[184:187], v[130:133]
	v_mfma_f32_16x16x32_bf16 v[118:121], v[150:153], v[192:195], v[118:121]
	v_mfma_f32_16x16x32_bf16 v[114:117], v[176:179], v[192:195], v[114:117]
	v_mfma_f32_16x16x32_bf16 v[102:105], v[150:153], v[200:203], v[102:105]
	v_mfma_f32_16x16x32_bf16 v[98:101], v[176:179], v[200:203], v[98:101]
	v_mfma_f32_16x16x32_bf16 v[86:89], v[150:153], v[208:211], v[86:89]
	v_mfma_f32_16x16x32_bf16 v[82:85], v[176:179], v[208:211], v[82:85]
	s_setprio 0
	s_barrier
; #define PG8_STAGE(bufoff, gbase, voff) do { _Pragma("unroll") for (int _i = 0; _i < 2; ++_i) \
;         __builtin_amdgcn_global_load_lds((const unsigned*)((const char*)(gbase) + (voff)[_i]), (PG8_LAS unsigned*)(lds + (bufoff) + ldsw + _i * 8192), 16, 0, 0); } while (0)
; #define PG8_LDA(dst, b, h) do { _Pragma("unroll") for (int m = 0; m < 4; ++m) _Pragma("unroll") for (int k = 0; k < 2; ++k) dst[m][k] = *(const PG8_LAS bf16x8*)(lds + PG8_SA(b, h) + aoff + m * 2048 + k * 1024); } while (0)
; #define PG8_MMA(ai, bj, At, Bt) do { __builtin_amdgcn_s_setprio(1); _Pragma("unroll") for (int m = 0; m < 4; ++m) _Pragma("unroll") for (int n = 0; n < 2; ++n) _Pragma("unroll") for (int k = 0; k < 2; ++k) \
;         acc[ai][bj][m][n] = __builtin_amdgcn_mfma_f32_16x16x32_bf16(Bt[n][k], At[m][k], acc[ai][bj][m][n], 0, 0, 0); __builtin_amdgcn_s_setprio(0); } while (0)
; #define PG8_WAIT_V(n) asm volatile("s_waitcnt vmcnt(" #n ")" ::: "memory")
; #define PG8_WAIT_L(n) asm volatile("s_waitcnt lgkmcnt(" #n ")" ::: "memory")
; #define PG8_BAR __builtin_amdgcn_s_barrier()
; #define PG8_SCHED __builtin_amdgcn_sched_barrier(0)
; template <class Epi, class Sched, bool ALIGN_EPI = false, bool SP2 = false>
; __device__ __forceinline__ void gemm_phase(PG8_LAS unsigned char* lds, const Gemm g, const Sched& S, const Epi& E) {
;     ...
;             PG8_LDA(At, 0, 1); PG8_STAGE(PG8_SB(0, 0), b2, voffB); PG8_STAGE(PG8_SB(0, 1), b2 + hstep, voffB); PG8_STAGE(PG8_SA(0, 0), a2, voffA);
;             PG8_WAIT_V(8); PG8_WAIT_L(0); PG8_BAR; PG8_MMA(1, 0, At, B0); PG8_MMA(1, 1, At, B1); PG8_BAR; PG8_SCHED;
	s_add_i32 s42, s68, s50
	v_lshl_add_u64 v[218:219], s[6:7], 0, v[156:157]
	s_mov_b32 m0, s42
	ds_read_b128 v[180:183], v216 offset:16384
	ds_read_b128 v[184:187], v216 offset:17408
	ds_read_b128 v[188:191], v216 offset:18432
	ds_read_b128 v[192:195], v216 offset:19456
	ds_read_b128 v[196:199], v216 offset:20480
	ds_read_b128 v[200:203], v216 offset:21504
	ds_read_b128 v[204:207], v216 offset:22528
	ds_read_b128 v[208:211], v216 offset:23552
	global_load_lds_dwordx4 v[218:219], off
	s_add_i32 m0, s42, 0x2000
	s_add_u32 s42, s6, 0x40000
	v_lshl_add_u64 v[222:223], s[6:7], 0, v[160:161]
	s_addc_u32 s43, s7, 0
	s_add_i32 s44, s69, s50
	global_load_lds_dwordx4 v[222:223], off
	v_lshl_add_u64 v[224:225], s[42:43], 0, v[156:157]
	s_mov_b32 m0, s44
	v_lshl_add_u64 v[226:227], s[36:37], 0, v[158:159]
	global_load_lds_dwordx4 v[224:225], off
	v_lshl_add_u64 v[224:225], s[42:43], 0, v[160:161]
	s_add_i32 m0, s44, 0x2000
	s_nop 0
	global_load_lds_dwordx4 v[224:225], off
	v_lshl_add_u64 v[224:225], s[36:37], 0, v[154:155]
	s_mov_b32 m0, s51
	s_nop 0
	global_load_lds_dwordx4 v[224:225], off
	s_mov_b32 m0, s52
	s_nop 0
	global_load_lds_dwordx4 v[226:227], off
	s_waitcnt vmcnt(8)
	s_waitcnt lgkmcnt(0)
	s_barrier
	s_setprio 1
	s_waitcnt lgkmcnt(0)
	v_mfma_f32_16x16x32_bf16 v[78:81], v[50:53], v[180:183], 0
	v_mfma_f32_16x16x32_bf16 v[74:77], v[66:69], v[180:183], 0
	v_mfma_f32_16x16x32_bf16 v[46:49], v[50:53], v[188:191], 0
	v_mfma_f32_16x16x32_bf16 v[42:45], v[66:69], v[188:191], 0
	v_mfma_f32_16x16x32_bf16 v[30:33], v[50:53], v[196:199], 0
	v_mfma_f32_16x16x32_bf16 v[26:29], v[66:69], v[196:199], 0
	v_mfma_f32_16x16x32_bf16 v[14:17], v[50:53], v[204:207], 0
	v_mfma_f32_16x16x32_bf16 v[10:13], v[66:69], v[204:207], 0
	v_mfma_f32_16x16x32_bf16 v[78:81], v[54:57], v[184:187], v[78:81]
	v_mfma_f32_16x16x32_bf16 v[74:77], v[70:73], v[184:187], v[74:77]
	v_mfma_f32_16x16x32_bf16 v[46:49], v[54:57], v[192:195], v[46:49]
	v_mfma_f32_16x16x32_bf16 v[42:45], v[70:73], v[192:195], v[42:45]
	v_mfma_f32_16x16x32_bf16 v[30:33], v[54:57], v[200:203], v[30:33]
	v_mfma_f32_16x16x32_bf16 v[26:29], v[70:73], v[200:203], v[26:29]
	v_mfma_f32_16x16x32_bf16 v[14:17], v[54:57], v[208:211], v[14:17]
	v_mfma_f32_16x16x32_bf16 v[10:13], v[70:73], v[208:211], v[10:13]
	s_setprio 0
	s_setprio 1
	v_mfma_f32_16x16x32_bf16 v[38:41], v[146:149], v[188:191], 0
	v_mfma_f32_16x16x32_bf16 v[34:37], v[172:175], v[188:191], 0
	v_mfma_f32_16x16x32_bf16 v[22:25], v[146:149], v[196:199], 0
	v_mfma_f32_16x16x32_bf16 v[18:21], v[172:175], v[196:199], 0
	v_mfma_f32_16x16x32_bf16 v[6:9], v[146:149], v[204:207], 0
	v_mfma_f32_16x16x32_bf16 v[2:5], v[172:175], v[204:207], 0
	v_mfma_f32_16x16x32_bf16 v[50:53], v[146:149], v[180:183], 0
	v_mfma_f32_16x16x32_bf16 v[54:57], v[172:175], v[180:183], 0
	v_mfma_f32_16x16x32_bf16 v[38:41], v[150:153], v[192:195], v[38:41]
	v_mfma_f32_16x16x32_bf16 v[34:37], v[176:179], v[192:195], v[34:37]
	v_mfma_f32_16x16x32_bf16 v[22:25], v[150:153], v[200:203], v[22:25]
	v_mfma_f32_16x16x32_bf16 v[18:21], v[176:179], v[200:203], v[18:21]
	v_mfma_f32_16x16x32_bf16 v[6:9], v[150:153], v[208:211], v[6:9]
	v_mfma_f32_16x16x32_bf16 v[2:5], v[176:179], v[208:211], v[2:5]
	v_mfma_f32_16x16x32_bf16 v[50:53], v[150:153], v[184:187], v[50:53]
	v_mfma_f32_16x16x32_bf16 v[54:57], v[176:179], v[184:187], v[54:57]
	s_setprio 0
	s_barrier
	s_branch .Lpz4_mid
	.p2alignl 6, 3212836864

; #define PG8_STAGE(bufoff, gbase, voff) do { _Pragma("unroll") for (int _i = 0; _i < 2; ++_i) \
;         __builtin_amdgcn_global_load_lds((const unsigned*)((const char*)(gbase) + (voff)[_i]), (PG8_LAS unsigned*)(lds + (bufoff) + ldsw + _i * 8192), 16, 0, 0); } while (0)
; #define PG8_LDA(dst, b, h) do { _Pragma("unroll") for (int m = 0; m < 4; ++m) _Pragma("unroll") for (int k = 0; k < 2; ++k) dst[m][k] = *(const PG8_LAS bf16x8*)(lds + PG8_SA(b, h) + aoff + m * 2048 + k * 1024); } while (0)
; #define PG8_LDB(dst, b, h) do { _Pragma("unroll") for (int n = 0; n < 2; ++n) _Pragma("unroll") for (int k = 0; k < 2; ++k) dst[n][k] = *(const PG8_LAS bf16x8*)(lds + PG8_SB(b, h) + boff + n * 2048 + k * 1024); } while (0)
; #define PG8_MMA(ai, bj, At, Bt) do { __builtin_amdgcn_s_setprio(1); _Pragma("unroll") for (int m = 0; m < 4; ++m) _Pragma("unroll") for (int n = 0; n < 2; ++n) _Pragma("unroll") for (int k = 0; k < 2; ++k) \
;         acc[ai][bj][m][n] = __builtin_amdgcn_mfma_f32_16x16x32_bf16(Bt[n][k], At[m][k], acc[ai][bj][m][n], 0, 0, 0); __builtin_amdgcn_s_setprio(0); } while (0)
; #define PG8_WAIT_V(n) asm volatile("s_waitcnt vmcnt(" #n ")" ::: "memory")
; #define PG8_WAIT_L(n) asm volatile("s_waitcnt lgkmcnt(" #n ")" ::: "memory")
; #define PG8_BAR __builtin_amdgcn_s_barrier()
; template <class Epi, class Sched, bool ALIGN_EPI = false, bool SP2 = false>
; __device__ __forceinline__ void gemm_phase(PG8_LAS unsigned char* lds, const Gemm g, const Sched& S, const Epi& E) {
;     ...
;             const char* a2 = last ? nA : cA + (size_t)(t + 2) * kstepA; const char* b2 = last ? nB : cB + (size_t)(t + 2) * kstep;
;             const char* a3 = a2 + kstepA; const char* b3 = b2 + kstep;
;             if (last && has_next) S.a_ready(nxt);
;             if constexpr (SP2) {
;             PG8_LDB(B0, 0, 0); PG8_LDB(B1, 0, 1); PG8_SCHED; PG8_LDA(At, 0, 0); PG8_STAGE(PG8_SA(1, 1), a1 + hstep, voffA);
;             PG8_WAIT_V(8); PG8_WAIT_L(0); PG8_BAR; PG8_MMA(0, 0, At, B0); PG8_MMA(0, 1, At, B1); PG8_BAR; PG8_SCHED;
;             if constexpr (Epi::PREFETCH) { if (t == tpf) E.prefetch(cur, wid, lane); }
;             PG8_LDA(At, 0, 1); PG8_STAGE(PG8_SB(0, 0), b2, voffB); PG8_STAGE(PG8_SB(0, 1), b2 + hstep, voffB); PG8_STAGE(PG8_SA(0, 0), a2, voffA);
;             PG8_WAIT_V(8); PG8_WAIT_L(0); PG8_BAR; PG8_MMA(1, 0, At, B0); PG8_MMA(1, 1, At, B1); PG8_BAR; PG8_SCHED;
.Lpz5_a:
	s_add_u32 s42, s30, s40
	s_addc_u32 s43, s31, s41
	s_add_u32 s42, s42, 0x100
	s_addc_u32 s43, s43, 0
	s_add_u32 s84, s29, s40
	s_addc_u32 s85, s35, s41
	s_cmpk_eq_i32 s40, 0x700
	s_cselect_b32 s45, s23, s43
	s_cselect_b32 s44, s81, s42
	s_cselect_b32 s43, s21, s85
	s_cselect_b32 s42, s82, s84
	s_mov_b32 m0, s55
	v_lshl_add_u64 v[232:233], s[42:43], 0, v[174:175]
	s_add_u32 s84, s42, 0x40000
	ds_read_b128 v[130:133], v197 offset:16384
	ds_read_b128 v[134:137], v197 offset:17408
	ds_read_b128 v[200:203], v197 offset:18432
	ds_read_b128 v[204:207], v197 offset:19456
	ds_read_b128 v[208:211], v197 offset:20480
	ds_read_b128 v[212:215], v197 offset:21504
	ds_read_b128 v[216:219], v197 offset:22528
	ds_read_b128 v[220:223], v197 offset:23552
	global_load_lds_dwordx4 v[232:233], off
	v_lshl_add_u64 v[234:235], s[42:43], 0, v[170:171]
	s_mov_b32 m0, s56
	s_addc_u32 s85, s43, 0
	global_load_lds_dwordx4 v[234:235], off
	v_lshl_add_u64 v[224:225], s[84:85], 0, v[174:175]
	s_mov_b32 m0, s57
	v_lshl_add_u64 v[236:237], s[44:45], 0, v[176:177]
	global_load_lds_dwordx4 v[224:225], off
	v_lshl_add_u64 v[224:225], s[84:85], 0, v[170:171]
	s_mov_b32 m0, s58
	v_lshl_add_u64 v[238:239], s[44:45], 0, v[172:173]
	global_load_lds_dwordx4 v[224:225], off
	s_mov_b32 m0, s54
	s_nop 0
	global_load_lds_dwordx4 v[236:237], off
	s_mov_b32 m0, s59
	s_nop 0
	global_load_lds_dwordx4 v[238:239], off
	s_waitcnt vmcnt(8)
	s_waitcnt lgkmcnt(0)
	s_barrier
	s_setprio 1
	s_waitcnt lgkmcnt(0)
	v_mfma_f32_16x16x32_bf16 v[62:65], v[154:157], v[130:133], 0
	v_mfma_f32_16x16x32_bf16 v[58:61], v[162:165], v[130:133], 0
	v_mfma_f32_16x16x32_bf16 v[46:49], v[154:157], v[200:203], 0
	v_mfma_f32_16x16x32_bf16 v[42:45], v[162:165], v[200:203], 0
	v_mfma_f32_16x16x32_bf16 v[30:33], v[154:157], v[208:211], 0
	v_mfma_f32_16x16x32_bf16 v[26:29], v[162:165], v[208:211], 0
	v_mfma_f32_16x16x32_bf16 v[14:17], v[154:157], v[216:219], 0
	v_mfma_f32_16x16x32_bf16 v[10:13], v[162:165], v[216:219], 0
	v_mfma_f32_16x16x32_bf16 v[62:65], v[158:161], v[134:137], v[62:65]
	v_mfma_f32_16x16x32_bf16 v[58:61], v[166:169], v[134:137], v[58:61]
	v_mfma_f32_16x16x32_bf16 v[46:49], v[158:161], v[204:207], v[46:49]
	v_mfma_f32_16x16x32_bf16 v[42:45], v[166:169], v[204:207], v[42:45]
	v_mfma_f32_16x16x32_bf16 v[30:33], v[158:161], v[212:215], v[30:33]
	v_mfma_f32_16x16x32_bf16 v[26:29], v[166:169], v[212:215], v[26:29]
	v_mfma_f32_16x16x32_bf16 v[14:17], v[158:161], v[220:223], v[14:17]
	v_mfma_f32_16x16x32_bf16 v[10:13], v[166:169], v[220:223], v[10:13]
	s_setprio 0
	s_setprio 1
	v_mfma_f32_16x16x32_bf16 v[54:57], v[138:141], v[130:133], 0
	v_mfma_f32_16x16x32_bf16 v[50:53], v[146:149], v[130:133], 0
	v_mfma_f32_16x16x32_bf16 v[38:41], v[138:141], v[200:203], 0
	v_mfma_f32_16x16x32_bf16 v[34:37], v[146:149], v[200:203], 0
	v_mfma_f32_16x16x32_bf16 v[22:25], v[138:141], v[208:211], 0
	v_mfma_f32_16x16x32_bf16 v[18:21], v[146:149], v[208:211], 0
	v_mfma_f32_16x16x32_bf16 v[6:9], v[138:141], v[216:219], 0
	v_mfma_f32_16x16x32_bf16 v[2:5], v[146:149], v[216:219], 0
	v_mfma_f32_16x16x32_bf16 v[54:57], v[142:145], v[134:137], v[54:57]
	v_mfma_f32_16x16x32_bf16 v[50:53], v[150:153], v[134:137], v[50:53]
	v_mfma_f32_16x16x32_bf16 v[38:41], v[142:145], v[204:207], v[38:41]
	v_mfma_f32_16x16x32_bf16 v[34:37], v[150:153], v[204:207], v[34:37]
	v_mfma_f32_16x16x32_bf16 v[22:25], v[142:145], v[212:215], v[22:25]
	v_mfma_f32_16x16x32_bf16 v[18:21], v[150:153], v[212:215], v[18:21]
	v_mfma_f32_16x16x32_bf16 v[6:9], v[142:145], v[220:223], v[6:9]
	v_mfma_f32_16x16x32_bf16 v[2:5], v[150:153], v[220:223], v[2:5]
	s_setprio 0
	s_barrier
	s_branch .Lpz5_mid
	.p2alignl 6, 3212836864

; #define PG8_STAGE(bufoff, gbase, voff) do { _Pragma("unroll") for (int _i = 0; _i < 2; ++_i) \
;         __builtin_amdgcn_global_load_lds((const unsigned*)((const char*)(gbase) + (voff)[_i]), (PG8_LAS unsigned*)(lds + (bufoff) + ldsw + _i * 8192), 16, 0, 0); } while (0)
; #define PG8_LDA(dst, b, h) do { _Pragma("unroll") for (int m = 0; m < 4; ++m) _Pragma("unroll") for (int k = 0; k < 2; ++k) dst[m][k] = *(const PG8_LAS bf16x8*)(lds + PG8_SA(b, h) + aoff + m * 2048 + k * 1024); } while (0)
; #define PG8_LDB(dst, b, h) do { _Pragma("unroll") for (int n = 0; n < 2; ++n) _Pragma("unroll") for (int k = 0; k < 2; ++k) dst[n][k] = *(const PG8_LAS bf16x8*)(lds + PG8_SB(b, h) + boff + n * 2048 + k * 1024); } while (0)
; #define PG8_MMA(ai, bj, At, Bt) do { __builtin_amdgcn_s_setprio(1); _Pragma("unroll") for (int m = 0; m < 4; ++m) _Pragma("unroll") for (int n = 0; n < 2; ++n) _Pragma("unroll") for (int k = 0; k < 2; ++k) \
;         acc[ai][bj][m][n] = __builtin_amdgcn_mfma_f32_16x16x32_bf16(Bt[n][k], At[m][k], acc[ai][bj][m][n], 0, 0, 0); __builtin_amdgcn_s_setprio(0); } while (0)
; #define PG8_WAIT_V(n) asm volatile("s_waitcnt vmcnt(" #n ")" ::: "memory")
; template <class Epi, class Sched, bool ALIGN_EPI = false, bool SP2 = false>
; __device__ __forceinline__ void gemm_phase(PG8_LAS unsigned char* lds, const Gemm g, const Sched& S, const Epi& E) {
;     ...
;             const bool last = (t == nt - 2);
;             const char* a1 = cA + (size_t)(t + 1) * kstepA;
;             const char* a2 = last ? nA : cA + (size_t)(t + 2) * kstepA; const char* b2 = last ? nB : cB + (size_t)(t + 2) * kstep;
;             const char* a3 = a2 + kstepA; const char* b3 = b2 + kstep;
;             if (last && has_next) S.a_ready(nxt);
;             if constexpr (SP2) {
;             PG8_LDB(B0, 0, 0); PG8_LDB(B1, 0, 1); PG8_SCHED; PG8_LDA(At, 0, 0); PG8_STAGE(PG8_SA(1, 1), a1 + hstep, voffA);
;             PG8_WAIT_V(8); PG8_WAIT_L(0); PG8_BAR; PG8_MMA(0, 0, At, B0); PG8_MMA(0, 1, At, B1); PG8_BAR; PG8_SCHED;
;             if constexpr (Epi::PREFETCH) { if (t == tpf) E.prefetch(cur, wid, lane); }
;             PG8_LDA(At, 0, 1); PG8_STAGE(PG8_SB(0, 0), b2, voffB); PG8_STAGE(PG8_SB(0, 1), b2 + hstep, voffB); PG8_STAGE(PG8_SA(0, 0), a2, voffA);
;             PG8_WAIT_V(8); PG8_WAIT_L(0); PG8_BAR; PG8_MMA(1, 0, At, B0); PG8_MMA(1, 1, At, B1); PG8_BAR; PG8_SCHED;
.LBB0_1068:
	s_add_u32 s35, s6, 0x100
	s_addc_u32 s36, s7, 0
	s_mov_b32 s37, -2
	s_waitcnt lgkmcnt(0)
	ds_read_b128 v[130:133], v192
	ds_read_b128 v[134:137], v192 offset:1024
	ds_read_b128 v[156:159], v192 offset:2048
	ds_read_b128 v[160:163], v192 offset:3072
	ds_read_b128 v[164:167], v193
	ds_read_b128 v[168:171], v193 offset:1024
	ds_read_b128 v[172:175], v193 offset:2048
	ds_read_b128 v[176:179], v193 offset:3072
	s_add_u32 s0, s4, 0x200
	s_addc_u32 s1, s5, 0
	s_cmp_eq_u32 s37, 40
	s_cselect_b32 s31, s27, s1
	s_cselect_b32 s30, s26, s0
	s_cselect_b32 s7, s29, s36
	s_cselect_b32 s6, s28, s35
	v_lshl_add_u64 v[188:189], s[4:5], 0, v[148:149]
	s_add_i32 m0, s45, 0xc000
	ds_read_b128 v[180:183], v194
	ds_read_b128 v[184:187], v194 offset:1024
	ds_read_b128 v[196:199], v194 offset:2048
	ds_read_b128 v[200:203], v194 offset:3072
	ds_read_b128 v[204:207], v194 offset:4096
	ds_read_b128 v[208:211], v194 offset:5120
	ds_read_b128 v[212:215], v194 offset:6144
	ds_read_b128 v[216:219], v194 offset:7168
	global_load_lds_dwordx4 v[188:189], off
	v_lshl_add_u64 v[188:189], s[4:5], 0, v[150:151]
	s_add_i32 m0, s45, 0xe000
	s_nop 0
	global_load_lds_dwordx4 v[188:189], off
	s_waitcnt vmcnt(8)
	s_waitcnt lgkmcnt(0)
	s_barrier
	s_setprio 1
	s_waitcnt lgkmcnt(0)
	v_mfma_f32_16x16x32_bf16 v[126:129], v[130:133], v[180:183], 0
	v_mfma_f32_16x16x32_bf16 v[122:125], v[156:159], v[180:183], 0
	v_mfma_f32_16x16x32_bf16 v[110:113], v[130:133], v[196:199], 0
	v_mfma_f32_16x16x32_bf16 v[106:109], v[156:159], v[196:199], 0
	v_mfma_f32_16x16x32_bf16 v[94:97], v[130:133], v[204:207], 0
	v_mfma_f32_16x16x32_bf16 v[90:93], v[156:159], v[204:207], 0
	v_mfma_f32_16x16x32_bf16 v[78:81], v[130:133], v[212:215], 0
	v_mfma_f32_16x16x32_bf16 v[74:77], v[156:159], v[212:215], 0
	v_mfma_f32_16x16x32_bf16 v[126:129], v[134:137], v[184:187], v[126:129]
	v_mfma_f32_16x16x32_bf16 v[122:125], v[160:163], v[184:187], v[122:125]
	v_mfma_f32_16x16x32_bf16 v[110:113], v[134:137], v[200:203], v[110:113]
	v_mfma_f32_16x16x32_bf16 v[106:109], v[160:163], v[200:203], v[106:109]
	v_mfma_f32_16x16x32_bf16 v[94:97], v[134:137], v[208:211], v[94:97]
	v_mfma_f32_16x16x32_bf16 v[90:93], v[160:163], v[208:211], v[90:93]
	v_mfma_f32_16x16x32_bf16 v[78:81], v[134:137], v[216:219], v[78:81]
	v_mfma_f32_16x16x32_bf16 v[74:77], v[160:163], v[216:219], v[74:77]
	s_setprio 0
	s_setprio 1
	v_mfma_f32_16x16x32_bf16 v[118:121], v[164:167], v[180:183], 0
	v_mfma_f32_16x16x32_bf16 v[114:117], v[172:175], v[180:183], 0
	v_mfma_f32_16x16x32_bf16 v[102:105], v[164:167], v[196:199], 0
	v_mfma_f32_16x16x32_bf16 v[98:101], v[172:175], v[196:199], 0
	v_mfma_f32_16x16x32_bf16 v[86:89], v[164:167], v[204:207], 0
	v_mfma_f32_16x16x32_bf16 v[82:85], v[172:175], v[204:207], 0
	v_mfma_f32_16x16x32_bf16 v[70:73], v[164:167], v[212:215], 0
	v_mfma_f32_16x16x32_bf16 v[66:69], v[172:175], v[212:215], 0
	v_mfma_f32_16x16x32_bf16 v[118:121], v[168:171], v[184:187], v[118:121]
	v_mfma_f32_16x16x32_bf16 v[114:117], v[176:179], v[184:187], v[114:117]
	v_mfma_f32_16x16x32_bf16 v[102:105], v[168:171], v[200:203], v[102:105]
	v_mfma_f32_16x16x32_bf16 v[98:101], v[176:179], v[200:203], v[98:101]
	v_mfma_f32_16x16x32_bf16 v[86:89], v[168:171], v[208:211], v[86:89]
	v_mfma_f32_16x16x32_bf16 v[82:85], v[176:179], v[208:211], v[82:85]
	v_mfma_f32_16x16x32_bf16 v[70:73], v[168:171], v[216:219], v[70:73]
	v_mfma_f32_16x16x32_bf16 v[66:69], v[176:179], v[216:219], v[66:69]
	s_setprio 0
	s_barrier
	s_add_i32 s4, s61, s44
	v_lshl_add_u64 v[188:189], s[6:7], 0, v[140:141]
	s_mov_b32 m0, s4
	ds_read_b128 v[180:183], v194 offset:16384
	ds_read_b128 v[184:187], v194 offset:17408
	ds_read_b128 v[196:199], v194 offset:18432
	ds_read_b128 v[200:203], v194 offset:19456
	ds_read_b128 v[204:207], v194 offset:20480
	ds_read_b128 v[208:211], v194 offset:21504
	ds_read_b128 v[212:215], v194 offset:22528
	ds_read_b128 v[216:219], v194 offset:23552
	global_load_lds_dwordx4 v[188:189], off
	s_add_i32 m0, s4, 0x2000
	s_add_u32 s4, s6, 0xb0000
	v_lshl_add_u64 v[220:221], s[6:7], 0, v[144:145]
	s_addc_u32 s5, s7, 0
	s_add_i32 s38, s62, s44
	global_load_lds_dwordx4 v[220:221], off
	v_lshl_add_u64 v[222:223], s[4:5], 0, v[140:141]
	s_mov_b32 m0, s38
	v_lshl_add_u64 v[224:225], s[30:31], 0, v[142:143]
	global_load_lds_dwordx4 v[222:223], off
	v_lshl_add_u64 v[222:223], s[4:5], 0, v[144:145]
	s_add_i32 m0, s38, 0x2000
	s_nop 0
	global_load_lds_dwordx4 v[222:223], off
	v_lshl_add_u64 v[222:223], s[30:31], 0, v[138:139]
	s_mov_b32 m0, s45
	s_nop 0
	global_load_lds_dwordx4 v[222:223], off
	s_mov_b32 m0, s46
	s_nop 0
	global_load_lds_dwordx4 v[224:225], off
	s_waitcnt vmcnt(8)
	s_waitcnt lgkmcnt(0)
	s_barrier
	s_setprio 1
	s_waitcnt lgkmcnt(0)
	v_mfma_f32_16x16x32_bf16 v[62:65], v[130:133], v[180:183], 0
	v_mfma_f32_16x16x32_bf16 v[58:61], v[156:159], v[180:183], 0
	v_mfma_f32_16x16x32_bf16 v[46:49], v[130:133], v[196:199], 0
	v_mfma_f32_16x16x32_bf16 v[42:45], v[156:159], v[196:199], 0
	v_mfma_f32_16x16x32_bf16 v[30:33], v[130:133], v[204:207], 0
	v_mfma_f32_16x16x32_bf16 v[26:29], v[156:159], v[204:207], 0
	v_mfma_f32_16x16x32_bf16 v[14:17], v[130:133], v[212:215], 0
	v_mfma_f32_16x16x32_bf16 v[10:13], v[156:159], v[212:215], 0
	v_mfma_f32_16x16x32_bf16 v[62:65], v[134:137], v[184:187], v[62:65]
	v_mfma_f32_16x16x32_bf16 v[58:61], v[160:163], v[184:187], v[58:61]
	v_mfma_f32_16x16x32_bf16 v[46:49], v[134:137], v[200:203], v[46:49]
	v_mfma_f32_16x16x32_bf16 v[42:45], v[160:163], v[200:203], v[42:45]
	v_mfma_f32_16x16x32_bf16 v[30:33], v[134:137], v[208:211], v[30:33]
	v_mfma_f32_16x16x32_bf16 v[26:29], v[160:163], v[208:211], v[26:29]
	v_mfma_f32_16x16x32_bf16 v[14:17], v[134:137], v[216:219], v[14:17]
	v_mfma_f32_16x16x32_bf16 v[10:13], v[160:163], v[216:219], v[10:13]
	s_setprio 0
	s_setprio 1
	v_mfma_f32_16x16x32_bf16 v[54:57], v[164:167], v[180:183], 0
	v_mfma_f32_16x16x32_bf16 v[50:53], v[172:175], v[180:183], 0
	v_mfma_f32_16x16x32_bf16 v[38:41], v[164:167], v[196:199], 0
	v_mfma_f32_16x16x32_bf16 v[34:37], v[172:175], v[196:199], 0
	v_mfma_f32_16x16x32_bf16 v[22:25], v[164:167], v[204:207], 0
	v_mfma_f32_16x16x32_bf16 v[18:21], v[172:175], v[204:207], 0
	v_mfma_f32_16x16x32_bf16 v[6:9], v[164:167], v[212:215], 0
	v_mfma_f32_16x16x32_bf16 v[2:5], v[172:175], v[212:215], 0
	v_mfma_f32_16x16x32_bf16 v[54:57], v[168:171], v[184:187], v[54:57]
	v_mfma_f32_16x16x32_bf16 v[50:53], v[176:179], v[184:187], v[50:53]
	v_mfma_f32_16x16x32_bf16 v[38:41], v[168:171], v[200:203], v[38:41]
	v_mfma_f32_16x16x32_bf16 v[34:37], v[176:179], v[200:203], v[34:37]
	v_mfma_f32_16x16x32_bf16 v[22:25], v[168:171], v[208:211], v[22:25]
	v_mfma_f32_16x16x32_bf16 v[18:21], v[176:179], v[208:211], v[18:21]
	v_mfma_f32_16x16x32_bf16 v[6:9], v[168:171], v[216:219], v[6:9]
	v_mfma_f32_16x16x32_bf16 v[2:5], v[176:179], v[216:219], v[2:5]
	s_setprio 0
	s_barrier
	s_branch .Lpz6_mid
	.p2alignl 6, 3212836864
